# window-branch loop: the 12 per-MFMA-group s_setprio flips deleted, so the one static priority raise of waves 4-7 persists through both layers
# baseline (speedup 1.0000x reference)
; #define LAS __attribute__((address_space(3)))
; __device__ __forceinline__ f32x16 mfma32(bf16x8 a, bf16x8 b, f32x16 c) { return __builtin_amdgcn_mfma_f32_32x32x16_bf16(a, b, c, 0, 0, 0); }
; #define FR_LOAD(S, KF, VF, X0, SP, VM) do { int tile_; const int sn_ = ((S) < nsteps) ? (S) : nsteps - 1; flash_desc<MODE>(sn_, list, base, t, t0, qi, hi, tile_, X0, SP, VM); \
;         flash_load(kb + (size_t)tile_ * 256, vb + (size_t)tile_ * 256, KF, VF); } while (0)
; __device__ __forceinline__ void flash_compute(bool domask, const bf16x8 (&kf)[4], const bf16x8 (&vf)[4], const bf16x8 (&q)[4], int x0, unsigned span, float& m, float& l, f32x16 (&O)[2]) {
;     f32x16 sc;
; #pragma unroll
;     for (int i = 0; i < 16; ++i) sc[i] = 0.f;
;     __builtin_amdgcn_s_setprio(1);
; #pragma unroll
;     for (int s = 0; s < 4; ++s) sc = mfma32(kf[s], q[s], sc);
;     __builtin_amdgcn_s_setprio(0);
;     if (domask) {
; #pragma unroll
;         for (int i = 0; i < 16; ++i) sc[i] = ((unsigned)(x0 + i + (i >= 8 ? 8 : 0)) <= span) ? sc[i] : -1e30f;
; template <int MODE> __device__ __forceinline__ void flash_run(const bf16x8* kb, const bf16x8* vb, const bf16x8 (&q)[4], int nsteps, const LAS unsigned* list, int base, int t, int t0, int qi, int hi, float& m, float& l, f32x16 (&O)[2]) {
;     if (nsteps <= 0) return;
;     bf16x8 kA[4], vA[4], kB[4], vB[4], kC[4], vC[4]; int x0A, x0B, x0C, vmA, vmB, vmC; unsigned spA, spB, spC;
;     ...
;     FR_LOAD(0, kA, vA, x0A, spA, vmA); FR_LOAD(1, kB, vB, x0B, spB, vmB);
; #pragma unroll 1
;     for (int s = 0; s < nsteps; s += 3) {
;         FR_LOAD(s + 2, kC, vC, x0C, spC, vmC); flash_compute(vmA != 0, kA, vA, q, x0A, spA, m, l, O); if (s + 1 >= nsteps) break;
;         FR_LOAD(s + 3, kA, vA, x0A, spA, vmA); flash_compute(vmB != 0, kB, vB, q, x0B, spB, m, l, O); if (s + 2 >= nsteps) break;
;         FR_LOAD(s + 4, kB, vB, x0B, spB, vmB); flash_compute(vmC != 0, kC, vC, q, x0C, spC, m, l, O);
;     }
.LBB0_869:
	s_add_i32 s1, s3, 2
	s_min_i32 s4, s1, s2
	s_add_i32 s6, s4, s0
	s_lshl_b64 s[12:13], s[6:7], 12
	v_lshl_add_u64 v[34:35], v[162:163], 0, s[12:13]
	v_lshl_add_u64 v[36:37], v[164:165], 0, s[12:13]
	global_load_dwordx4 v[158:161], v[34:35], off
	global_load_dwordx4 v[154:157], v[34:35], off offset:1024
	global_load_dwordx4 v[150:153], v[34:35], off offset:2048
	global_load_dwordx4 v[146:149], v[34:35], off offset:3072
	global_load_dwordx4 v[142:145], v[36:37], off
	global_load_dwordx4 v[138:141], v[36:37], off offset:1024
	global_load_dwordx4 v[134:137], v[36:37], off offset:2048
	global_load_dwordx4 v[130:133], v[36:37], off offset:3072
	s_cmp_eq_u32 s17, 0
	s_waitcnt vmcnt(15)
	v_mfma_f32_32x32x16_bf16 v[34:49], v[94:97], v[50:53], 0
	s_waitcnt vmcnt(14)
	v_mfma_f32_32x32x16_bf16 v[34:49], v[90:93], v[62:65], v[34:49]
	s_waitcnt vmcnt(13)
	v_mfma_f32_32x32x16_bf16 v[34:49], v[82:85], v[58:61], v[34:49]
	s_waitcnt vmcnt(12)
	v_mfma_f32_32x32x16_bf16 v[34:49], v[86:89], v[54:57], v[34:49]
	s_cbranch_scc1 .LBB0_871
	v_sub_u32_e32 v82, s5, v242
	v_add_u32_e32 v83, v82, v167
	v_cmp_gt_u32_e32 vcc, s65, v83
	v_add_u32_e32 v82, v82, v218
	s_nop 5
	v_cndmask_b32_e32 v34, v249, v34, vcc
	v_cmp_lt_u32_e32 vcc, s55, v82
	v_add_u32_e32 v82, 0xfffffe02, v83
	s_nop 0
	v_cndmask_b32_e32 v35, v249, v35, vcc
	v_cmp_lt_u32_e32 vcc, s55, v82
	v_add_u32_e32 v82, 0xfffffe03, v83
	s_nop 0
	v_cndmask_b32_e32 v36, v249, v36, vcc
	v_cmp_lt_u32_e32 vcc, s55, v82
	v_add_u32_e32 v82, 0xfffffe04, v83
	s_nop 0
	v_cndmask_b32_e32 v37, v249, v37, vcc
	v_cmp_lt_u32_e32 vcc, s55, v82
	v_add_u32_e32 v82, 0xfffffe05, v83
	s_nop 0
	v_cndmask_b32_e32 v38, v249, v38, vcc
	v_cmp_lt_u32_e32 vcc, s55, v82
	v_add_u32_e32 v82, 0xfffffe06, v83
	s_nop 0
	v_cndmask_b32_e32 v39, v249, v39, vcc
	v_cmp_lt_u32_e32 vcc, s55, v82
	v_add_u32_e32 v82, 0xfffffe07, v83
	s_nop 0
	v_cndmask_b32_e32 v40, v249, v40, vcc
	v_cmp_lt_u32_e32 vcc, s55, v82
	v_add_u32_e32 v82, 0xfffffe10, v83
	s_nop 0
	v_cndmask_b32_e32 v41, v249, v41, vcc
	v_cmp_lt_u32_e32 vcc, s55, v82
	v_add_u32_e32 v82, 0xfffffe11, v83
	s_nop 0
	v_cndmask_b32_e32 v42, v249, v42, vcc
	v_cmp_lt_u32_e32 vcc, s55, v82
	v_add_u32_e32 v82, 0xfffffe12, v83
	s_nop 0
	v_cndmask_b32_e32 v43, v249, v43, vcc
	v_cmp_lt_u32_e32 vcc, s55, v82
	v_add_u32_e32 v82, 0xfffffe13, v83
	s_nop 0
	v_cndmask_b32_e32 v44, v249, v44, vcc
	v_cmp_lt_u32_e32 vcc, s55, v82
	v_add_u32_e32 v82, 0xfffffe14, v83
	s_nop 0
	v_cndmask_b32_e32 v45, v249, v45, vcc
	v_cmp_lt_u32_e32 vcc, s55, v82
	v_add_u32_e32 v82, 0xfffffe15, v83
	s_nop 0
	v_cndmask_b32_e32 v46, v249, v46, vcc
	v_cmp_lt_u32_e32 vcc, s55, v82
	v_add_u32_e32 v82, 0xfffffe16, v83
	s_nop 0
	v_cndmask_b32_e32 v47, v249, v47, vcc
	v_cmp_lt_u32_e32 vcc, s55, v82
	v_add_u32_e32 v82, 0xfffffe17, v83
	s_nop 0
	v_cndmask_b32_e32 v48, v249, v48, vcc
	v_cmp_lt_u32_e32 vcc, s55, v82
	s_nop 1
	v_cndmask_b32_e32 v49, v249, v49, vcc

; __device__ __forceinline__ float ex2(float x) { return __builtin_amdgcn_exp2f(x); }
; __device__ __forceinline__ void flash_compute(bool domask, const bf16x8 (&kf)[4], const bf16x8 (&vf)[4], const bf16x8 (&q)[4], int x0, unsigned span, float& m, float& l, f32x16 (&O)[2]) {
;     f32x16 sc;
; #pragma unroll
;     for (int i = 0; i < 16; ++i) sc[i] = 0.f;
;     __builtin_amdgcn_s_setprio(1);
; #pragma unroll
;     for (int s = 0; s < 4; ++s) sc = mfma32(kf[s], q[s], sc);
;     __builtin_amdgcn_s_setprio(0);
;     if (domask) {
; #pragma unroll
;         for (int i = 0; i < 16; ++i) sc[i] = ((unsigned)(x0 + i + (i >= 8 ? 8 : 0)) <= span) ? sc[i] : -1e30f;
;     }
;     const float a0 = fmaxf(fmaxf(sc[0], sc[1]), sc[2]), a1 = fmaxf(fmaxf(sc[3], sc[4]), sc[5]), a2 = fmaxf(fmaxf(sc[6], sc[7]), sc[8]), a3 = fmaxf(fmaxf(sc[9], sc[10]), sc[11]), a4 = fmaxf(fmaxf(sc[12], sc[13]), sc[14]);
;     float mx = fmaxf(fmaxf(fmaxf(a0, a1), fmaxf(a2, a3)), fmaxf(a4, sc[15]));
;     mx = xhalf_max(mx);
;     const bool upd = mx > m + SM_THR;
;     if (__ballot(upd) != 0ull) {
;         const float mn = upd ? mx : m, alpha = ex2(m - mn); l *= alpha; O[0] = O[0] * alpha; O[1] = O[1] * alpha; m = mn;
;     }
;     const float msub = (m < -1e29f) ? 0.f : m;
;     const f32x16 d = sc - msub;
;     float p[16], ps = 0.f;
; #pragma unroll
;     for (int i = 0; i < 16; ++i) { p[i] = ex2(d[i]); ps += p[i]; }
;     l += ps;
;     const bf16x8 pb0 = pack_p(p), pb1 = pack_p(p + 8);
;     __builtin_amdgcn_s_setprio(1);
;     O[0] = mfma32(vf[0], pb0, O[0]); O[1] = mfma32(vf[1], pb0, O[1]);
;     O[0] = mfma32(vf[2], pb1, O[0]); O[1] = mfma32(vf[3], pb1, O[1]);
;     __builtin_amdgcn_s_setprio(0);
; }
; template <int MODE> __device__ __forceinline__ void flash_run(const bf16x8* kb, const bf16x8* vb, const bf16x8 (&q)[4], int nsteps, const LAS unsigned* list, int base, int t, int t0, int qi, int hi, float& m, float& l, f32x16 (&O)[2]) {
;     ...
;         FR_LOAD(s + 2, kC, vC, x0C, spC, vmC); flash_compute(vmA != 0, kA, vA, q, x0A, spA, m, l, O); if (s + 1 >= nsteps) break;
;         FR_LOAD(s + 3, kA, vA, x0A, spA, vmA); flash_compute(vmB != 0, kB, vB, q, x0B, spB, m, l, O); if (s + 2 >= nsteps) break;
;         FR_LOAD(s + 4, kB, vB, x0B, spB, vmB); flash_compute(vmC != 0, kC, vC, q, x0C, spC, m, l, O);
.LBB0_873:
	v_cmp_ngt_f32_e32 vcc, s66, v168
	s_nop 1
	v_cndmask_b32_e32 v82, 0, v168, vcc
	v_sub_f32_e32 v34, v34, v82
	v_sub_f32_e32 v35, v35, v82
	v_exp_f32_e32 v34, v34
	v_sub_f32_e32 v36, v36, v82
	v_exp_f32_e32 v35, v35
	v_sub_f32_e32 v37, v37, v82
	v_exp_f32_e32 v36, v36
	v_sub_f32_e32 v38, v38, v82
	v_exp_f32_e32 v37, v37
	v_sub_f32_e32 v49, v49, v82
	v_sub_f32_e32 v48, v48, v82
	v_sub_f32_e32 v47, v47, v82
	v_sub_f32_e32 v46, v46, v82
	v_sub_f32_e32 v45, v45, v82
	v_sub_f32_e32 v44, v44, v82
	v_sub_f32_e32 v43, v43, v82
	v_sub_f32_e32 v42, v42, v82
	v_sub_f32_e32 v41, v41, v82
	v_sub_f32_e32 v40, v40, v82
	v_sub_f32_e32 v39, v39, v82
	v_add_f32_e32 v82, 0, v34
	v_exp_f32_e32 v38, v38
	v_add_f32_e32 v82, v35, v82
	v_exp_f32_e32 v39, v39
	v_add_f32_e32 v82, v36, v82
	v_exp_f32_e32 v40, v40
	v_add_f32_e32 v82, v37, v82
	v_exp_f32_e32 v41, v41
	v_add_f32_e32 v82, v38, v82
	v_exp_f32_e32 v42, v42
	v_add_f32_e32 v82, v39, v82
	v_exp_f32_e32 v43, v43
	v_add_f32_e32 v82, v40, v82
	v_exp_f32_e32 v44, v44
	v_add_f32_e32 v82, v41, v82
	v_exp_f32_e32 v45, v45
	v_add_f32_e32 v82, v42, v82
	v_exp_f32_e32 v46, v46
	v_add_f32_e32 v82, v43, v82
	v_exp_f32_e32 v47, v47
	v_add_f32_e32 v82, v44, v82
	v_exp_f32_e32 v48, v48
	v_add_f32_e32 v82, v45, v82
	v_exp_f32_e32 v49, v49
	v_add_f32_e32 v82, v46, v82
	v_add_f32_e32 v82, v47, v82
	v_add_f32_e32 v82, v48, v82
	v_add_f32_e32 v82, v49, v82
	v_add_f32_e32 v166, v166, v82
	v_cvt_pk_bf16_f32 v34, v34, v35
	v_cvt_pk_bf16_f32 v35, v36, v37
	v_cvt_pk_bf16_f32 v36, v38, v39
	v_cvt_pk_bf16_f32 v37, v40, v41
	v_cvt_pk_bf16_f32 v38, v42, v43
	v_cvt_pk_bf16_f32 v39, v44, v45
	v_cvt_pk_bf16_f32 v40, v46, v47
	v_cvt_pk_bf16_f32 v41, v48, v49
	s_waitcnt vmcnt(11)
	v_mfma_f32_32x32x16_bf16 v[18:33], v[74:77], v[34:37], v[18:33]
	s_waitcnt vmcnt(10)
	v_mfma_f32_32x32x16_bf16 v[2:17], v[70:73], v[34:37], v[2:17]
	s_waitcnt vmcnt(9)
	v_mfma_f32_32x32x16_bf16 v[18:33], v[66:69], v[38:41], v[18:33]
	s_waitcnt vmcnt(8)
	v_mfma_f32_32x32x16_bf16 v[2:17], v[78:81], v[38:41], v[2:17]
	s_cmp_ge_i32 s3, s2
	s_mov_b64 s[12:13], -1
	s_cbranch_scc1 .LBB0_868
	s_add_i32 s4, s3, 3
	s_min_i32 s4, s4, s2
	s_add_i32 s4, s4, s0
	s_mov_b32 s5, s7
	s_lshl_b64 s[12:13], s[4:5], 12
	v_lshl_add_u64 v[34:35], v[162:163], 0, s[12:13]
	v_lshl_add_u64 v[36:37], v[164:165], 0, s[12:13]
	global_load_dwordx4 v[94:97], v[34:35], off
	global_load_dwordx4 v[90:93], v[34:35], off offset:1024
	global_load_dwordx4 v[82:85], v[34:35], off offset:2048
	global_load_dwordx4 v[86:89], v[34:35], off offset:3072
	global_load_dwordx4 v[74:77], v[36:37], off
	global_load_dwordx4 v[70:73], v[36:37], off offset:1024
	global_load_dwordx4 v[66:69], v[36:37], off offset:2048
	global_load_dwordx4 v[78:81], v[36:37], off offset:3072
	s_cmp_eq_u32 s11, 0
	s_waitcnt vmcnt(23)
	v_mfma_f32_32x32x16_bf16 v[34:49], v[114:117], v[50:53], 0
	s_waitcnt vmcnt(22)
	v_mfma_f32_32x32x16_bf16 v[34:49], v[118:121], v[62:65], v[34:49]
	s_waitcnt vmcnt(21)
	v_mfma_f32_32x32x16_bf16 v[34:49], v[122:125], v[58:61], v[34:49]
	s_waitcnt vmcnt(20)
	v_mfma_f32_32x32x16_bf16 v[34:49], v[126:129], v[54:57], v[34:49]
	s_cbranch_scc1 .LBB0_876
	v_sub_u32_e32 v114, s10, v242
	v_add_u32_e32 v115, v114, v167
	v_cmp_gt_u32_e32 vcc, s65, v115
	v_add_u32_e32 v114, v114, v218
	s_nop 5
	v_cndmask_b32_e32 v34, v249, v34, vcc
	v_cmp_lt_u32_e32 vcc, s55, v114
	v_add_u32_e32 v114, 0xfffffe02, v115
	s_nop 0
	v_cndmask_b32_e32 v35, v249, v35, vcc
	v_cmp_lt_u32_e32 vcc, s55, v114
	v_add_u32_e32 v114, 0xfffffe03, v115
	s_nop 0
	v_cndmask_b32_e32 v36, v249, v36, vcc
	v_cmp_lt_u32_e32 vcc, s55, v114
	v_add_u32_e32 v114, 0xfffffe04, v115
	s_nop 0
	v_cndmask_b32_e32 v37, v249, v37, vcc
	v_cmp_lt_u32_e32 vcc, s55, v114
	v_add_u32_e32 v114, 0xfffffe05, v115
	s_nop 0
	v_cndmask_b32_e32 v38, v249, v38, vcc
	v_cmp_lt_u32_e32 vcc, s55, v114
	v_add_u32_e32 v114, 0xfffffe06, v115
	s_nop 0
	v_cndmask_b32_e32 v39, v249, v39, vcc
	v_cmp_lt_u32_e32 vcc, s55, v114
	v_add_u32_e32 v114, 0xfffffe07, v115
	s_nop 0
	v_cndmask_b32_e32 v40, v249, v40, vcc
	v_cmp_lt_u32_e32 vcc, s55, v114
	v_add_u32_e32 v114, 0xfffffe10, v115
	s_nop 0
	v_cndmask_b32_e32 v41, v249, v41, vcc
	v_cmp_lt_u32_e32 vcc, s55, v114
	v_add_u32_e32 v114, 0xfffffe11, v115
	s_nop 0
	v_cndmask_b32_e32 v42, v249, v42, vcc
	v_cmp_lt_u32_e32 vcc, s55, v114
	v_add_u32_e32 v114, 0xfffffe12, v115
	s_nop 0
	v_cndmask_b32_e32 v43, v249, v43, vcc
	v_cmp_lt_u32_e32 vcc, s55, v114
	v_add_u32_e32 v114, 0xfffffe13, v115
	s_nop 0
	v_cndmask_b32_e32 v44, v249, v44, vcc
	v_cmp_lt_u32_e32 vcc, s55, v114
	v_add_u32_e32 v114, 0xfffffe14, v115
	s_nop 0
	v_cndmask_b32_e32 v45, v249, v45, vcc
	v_cmp_lt_u32_e32 vcc, s55, v114
	v_add_u32_e32 v114, 0xfffffe15, v115
	s_nop 0
	v_cndmask_b32_e32 v46, v249, v46, vcc
	v_cmp_lt_u32_e32 vcc, s55, v114
	v_add_u32_e32 v114, 0xfffffe16, v115
	s_nop 0
	v_cndmask_b32_e32 v47, v249, v47, vcc
	v_cmp_lt_u32_e32 vcc, s55, v114
	v_add_u32_e32 v114, 0xfffffe17, v115
	s_nop 0
	v_cndmask_b32_e32 v48, v249, v48, vcc
	v_cmp_lt_u32_e32 vcc, s55, v114
	s_nop 1
	v_cndmask_b32_e32 v49, v249, v49, vcc

; __device__ __forceinline__ float ex2(float x) { return __builtin_amdgcn_exp2f(x); }
; __device__ __forceinline__ void flash_compute(bool domask, const bf16x8 (&kf)[4], const bf16x8 (&vf)[4], const bf16x8 (&q)[4], int x0, unsigned span, float& m, float& l, f32x16 (&O)[2]) {
;     f32x16 sc;
; #pragma unroll
;     for (int i = 0; i < 16; ++i) sc[i] = 0.f;
;     __builtin_amdgcn_s_setprio(1);
; #pragma unroll
;     for (int s = 0; s < 4; ++s) sc = mfma32(kf[s], q[s], sc);
;     __builtin_amdgcn_s_setprio(0);
;     if (domask) {
; #pragma unroll
;         for (int i = 0; i < 16; ++i) sc[i] = ((unsigned)(x0 + i + (i >= 8 ? 8 : 0)) <= span) ? sc[i] : -1e30f;
;     }
;     const float a0 = fmaxf(fmaxf(sc[0], sc[1]), sc[2]), a1 = fmaxf(fmaxf(sc[3], sc[4]), sc[5]), a2 = fmaxf(fmaxf(sc[6], sc[7]), sc[8]), a3 = fmaxf(fmaxf(sc[9], sc[10]), sc[11]), a4 = fmaxf(fmaxf(sc[12], sc[13]), sc[14]);
;     float mx = fmaxf(fmaxf(fmaxf(a0, a1), fmaxf(a2, a3)), fmaxf(a4, sc[15]));
;     mx = xhalf_max(mx);
;     const bool upd = mx > m + SM_THR;
;     if (__ballot(upd) != 0ull) {
;         const float mn = upd ? mx : m, alpha = ex2(m - mn); l *= alpha; O[0] = O[0] * alpha; O[1] = O[1] * alpha; m = mn;
;     }
;     const float msub = (m < -1e29f) ? 0.f : m;
;     const f32x16 d = sc - msub;
;     float p[16], ps = 0.f;
; #pragma unroll
;     for (int i = 0; i < 16; ++i) { p[i] = ex2(d[i]); ps += p[i]; }
;     l += ps;
;     const bf16x8 pb0 = pack_p(p), pb1 = pack_p(p + 8);
;     __builtin_amdgcn_s_setprio(1);
;     O[0] = mfma32(vf[0], pb0, O[0]); O[1] = mfma32(vf[1], pb0, O[1]);
;     O[0] = mfma32(vf[2], pb1, O[0]); O[1] = mfma32(vf[3], pb1, O[1]);
;     __builtin_amdgcn_s_setprio(0);
; }
; template <int MODE> __device__ __forceinline__ void flash_run(const bf16x8* kb, const bf16x8* vb, const bf16x8 (&q)[4], int nsteps, const LAS unsigned* list, int base, int t, int t0, int qi, int hi, float& m, float& l, f32x16 (&O)[2]) {
;     ...
;         FR_LOAD(s + 2, kC, vC, x0C, spC, vmC); flash_compute(vmA != 0, kA, vA, q, x0A, spA, m, l, O); if (s + 1 >= nsteps) break;
;         FR_LOAD(s + 3, kA, vA, x0A, spA, vmA); flash_compute(vmB != 0, kB, vB, q, x0B, spB, m, l, O); if (s + 2 >= nsteps) break;
;         FR_LOAD(s + 4, kB, vB, x0B, spB, vmB); flash_compute(vmC != 0, kC, vC, q, x0C, spC, m, l, O);
.LBB0_878:
	v_cmp_ngt_f32_e32 vcc, s66, v168
	s_nop 1
	v_cndmask_b32_e32 v114, 0, v168, vcc
	v_sub_f32_e32 v34, v34, v114
	v_sub_f32_e32 v35, v35, v114
	v_exp_f32_e32 v34, v34
	v_sub_f32_e32 v36, v36, v114
	v_exp_f32_e32 v35, v35
	v_sub_f32_e32 v37, v37, v114
	v_exp_f32_e32 v36, v36
	v_sub_f32_e32 v38, v38, v114
	v_exp_f32_e32 v37, v37
	v_sub_f32_e32 v49, v49, v114
	v_sub_f32_e32 v48, v48, v114
	v_sub_f32_e32 v47, v47, v114
	v_sub_f32_e32 v46, v46, v114
	v_sub_f32_e32 v45, v45, v114
	v_sub_f32_e32 v44, v44, v114
	v_sub_f32_e32 v43, v43, v114
	v_sub_f32_e32 v42, v42, v114
	v_sub_f32_e32 v41, v41, v114
	v_sub_f32_e32 v40, v40, v114
	v_sub_f32_e32 v39, v39, v114
	v_add_f32_e32 v114, 0, v34
	v_exp_f32_e32 v38, v38
	v_add_f32_e32 v114, v35, v114
	v_exp_f32_e32 v39, v39
	v_add_f32_e32 v114, v36, v114
	v_exp_f32_e32 v40, v40
	v_add_f32_e32 v114, v37, v114
	v_exp_f32_e32 v41, v41
	v_add_f32_e32 v114, v38, v114
	v_exp_f32_e32 v42, v42
	v_add_f32_e32 v114, v39, v114
	v_exp_f32_e32 v43, v43
	v_add_f32_e32 v114, v40, v114
	v_exp_f32_e32 v44, v44
	v_add_f32_e32 v114, v41, v114
	v_exp_f32_e32 v45, v45
	v_add_f32_e32 v114, v42, v114
	v_exp_f32_e32 v46, v46
	v_add_f32_e32 v114, v43, v114
	v_exp_f32_e32 v47, v47
	v_add_f32_e32 v114, v44, v114
	v_exp_f32_e32 v48, v48
	v_add_f32_e32 v114, v45, v114
	v_exp_f32_e32 v49, v49
	v_add_f32_e32 v114, v46, v114
	v_add_f32_e32 v114, v47, v114
	v_add_f32_e32 v114, v48, v114
	v_add_f32_e32 v114, v49, v114
	v_add_f32_e32 v166, v166, v114
	v_cvt_pk_bf16_f32 v34, v34, v35
	v_cvt_pk_bf16_f32 v35, v36, v37
	v_cvt_pk_bf16_f32 v36, v38, v39
	v_cvt_pk_bf16_f32 v37, v40, v41
	v_cvt_pk_bf16_f32 v38, v42, v43
	v_cvt_pk_bf16_f32 v39, v44, v45
	v_cvt_pk_bf16_f32 v40, v46, v47
	v_cvt_pk_bf16_f32 v41, v48, v49
	s_waitcnt vmcnt(19)
	v_mfma_f32_32x32x16_bf16 v[18:33], v[98:101], v[34:37], v[18:33]
	s_waitcnt vmcnt(18)
	v_mfma_f32_32x32x16_bf16 v[2:17], v[102:105], v[34:37], v[2:17]
	s_waitcnt vmcnt(17)
	v_mfma_f32_32x32x16_bf16 v[18:33], v[106:109], v[38:41], v[18:33]
	s_waitcnt vmcnt(16)
	v_mfma_f32_32x32x16_bf16 v[2:17], v[110:113], v[38:41], v[2:17]
	s_cmp_gt_i32 s1, s2
	s_mov_b64 s[12:13], -1
	s_cbranch_scc1 .LBB0_884
	s_lshl_b32 s5, s6, 5
	s_or_b32 s6, s5, 31
	s_cmp_gt_i32 s6, s97
	s_cselect_b64 s[10:11], -1, 0
	s_cmp_lt_i32 s5, s16
	s_cselect_b64 s[12:13], -1, 0
	s_add_i32 s3, s3, 4
	s_min_i32 s3, s3, s2
	s_add_i32 s6, s3, s0
	s_lshl_b64 s[18:19], s[6:7], 12
	v_lshl_add_u64 v[34:35], v[162:163], 0, s[18:19]
	v_lshl_add_u64 v[36:37], v[164:165], 0, s[18:19]
	global_load_dwordx4 v[114:117], v[34:35], off
	global_load_dwordx4 v[118:121], v[34:35], off offset:1024
	global_load_dwordx4 v[122:125], v[34:35], off offset:2048
	global_load_dwordx4 v[126:129], v[34:35], off offset:3072
	global_load_dwordx4 v[98:101], v[36:37], off
	global_load_dwordx4 v[102:105], v[36:37], off offset:1024
	global_load_dwordx4 v[106:109], v[36:37], off offset:2048
	global_load_dwordx4 v[110:113], v[36:37], off offset:3072
	s_or_b64 s[10:11], s[10:11], s[12:13]
	s_waitcnt vmcnt(23)
	v_mfma_f32_32x32x16_bf16 v[34:49], v[158:161], v[50:53], 0
	s_waitcnt vmcnt(22)
	v_mfma_f32_32x32x16_bf16 v[34:49], v[154:157], v[62:65], v[34:49]
	s_waitcnt vmcnt(21)
	v_mfma_f32_32x32x16_bf16 v[34:49], v[150:153], v[58:61], v[34:49]
	s_waitcnt vmcnt(20)
	v_mfma_f32_32x32x16_bf16 v[34:49], v[146:149], v[54:57], v[34:49]
	s_andn2_b64 vcc, exec, s[10:11]
	s_cbranch_vccnz .LBB0_881
	v_sub_u32_e32 v146, s5, v242
	v_add_u32_e32 v147, v146, v167
	v_cmp_gt_u32_e32 vcc, s65, v147
	v_add_u32_e32 v146, v146, v218
	s_nop 4
	v_cndmask_b32_e32 v34, v249, v34, vcc
	v_cmp_lt_u32_e32 vcc, s55, v146
	v_add_u32_e32 v146, 0xfffffe02, v147
	s_nop 0
	v_cndmask_b32_e32 v35, v249, v35, vcc
	v_cmp_lt_u32_e32 vcc, s55, v146
	v_add_u32_e32 v146, 0xfffffe03, v147
	s_nop 0
	v_cndmask_b32_e32 v36, v249, v36, vcc
	v_cmp_lt_u32_e32 vcc, s55, v146
	v_add_u32_e32 v146, 0xfffffe04, v147
	s_nop 0
	v_cndmask_b32_e32 v37, v249, v37, vcc
	v_cmp_lt_u32_e32 vcc, s55, v146
	v_add_u32_e32 v146, 0xfffffe05, v147
	s_nop 0
	v_cndmask_b32_e32 v38, v249, v38, vcc
	v_cmp_lt_u32_e32 vcc, s55, v146
	v_add_u32_e32 v146, 0xfffffe06, v147
	s_nop 0
	v_cndmask_b32_e32 v39, v249, v39, vcc
	v_cmp_lt_u32_e32 vcc, s55, v146
	v_add_u32_e32 v146, 0xfffffe07, v147
	s_nop 0
	v_cndmask_b32_e32 v40, v249, v40, vcc
	v_cmp_lt_u32_e32 vcc, s55, v146
	v_add_u32_e32 v146, 0xfffffe10, v147
	s_nop 0
	v_cndmask_b32_e32 v41, v249, v41, vcc
	v_cmp_lt_u32_e32 vcc, s55, v146
	v_add_u32_e32 v146, 0xfffffe11, v147
	s_nop 0
	v_cndmask_b32_e32 v42, v249, v42, vcc
	v_cmp_lt_u32_e32 vcc, s55, v146
	v_add_u32_e32 v146, 0xfffffe12, v147
	s_nop 0
	v_cndmask_b32_e32 v43, v249, v43, vcc
	v_cmp_lt_u32_e32 vcc, s55, v146
	v_add_u32_e32 v146, 0xfffffe13, v147
	s_nop 0
	v_cndmask_b32_e32 v44, v249, v44, vcc
	v_cmp_lt_u32_e32 vcc, s55, v146
	v_add_u32_e32 v146, 0xfffffe14, v147
	s_nop 0
	v_cndmask_b32_e32 v45, v249, v45, vcc
	v_cmp_lt_u32_e32 vcc, s55, v146
	v_add_u32_e32 v146, 0xfffffe15, v147
	s_nop 0
	v_cndmask_b32_e32 v46, v249, v46, vcc
	v_cmp_lt_u32_e32 vcc, s55, v146
	v_add_u32_e32 v146, 0xfffffe16, v147
	s_nop 0
	v_cndmask_b32_e32 v47, v249, v47, vcc
	v_cmp_lt_u32_e32 vcc, s55, v146
	v_add_u32_e32 v146, 0xfffffe17, v147
	s_nop 0
	v_cndmask_b32_e32 v48, v249, v48, vcc
	v_cmp_lt_u32_e32 vcc, s55, v146
	s_nop 1
	v_cndmask_b32_e32 v49, v249, v49, vcc

; __device__ __forceinline__ float ex2(float x) { return __builtin_amdgcn_exp2f(x); }
; __device__ __forceinline__ float xhalf_max(float v) { const auto r = __builtin_amdgcn_permlane32_swap(__float_as_uint(v), __float_as_uint(v), false, false); return fmaxf(__uint_as_float(r[0]), __uint_as_float(r[1])); }
; __device__ __forceinline__ f32x16 mfma32(bf16x8 a, bf16x8 b, f32x16 c) { return __builtin_amdgcn_mfma_f32_32x32x16_bf16(a, b, c, 0, 0, 0); }
; __device__ __forceinline__ void flash_compute(bool domask, const bf16x8 (&kf)[4], const bf16x8 (&vf)[4], const bf16x8 (&q)[4], int x0, unsigned span, float& m, float& l, f32x16 (&O)[2]) {
;     ...
;     const float a0 = fmaxf(fmaxf(sc[0], sc[1]), sc[2]), a1 = fmaxf(fmaxf(sc[3], sc[4]), sc[5]), a2 = fmaxf(fmaxf(sc[6], sc[7]), sc[8]), a3 = fmaxf(fmaxf(sc[9], sc[10]), sc[11]), a4 = fmaxf(fmaxf(sc[12], sc[13]), sc[14]);
;     float mx = fmaxf(fmaxf(fmaxf(a0, a1), fmaxf(a2, a3)), fmaxf(a4, sc[15]));
;     mx = xhalf_max(mx);
;     const bool upd = mx > m + SM_THR;
;     if (__ballot(upd) != 0ull) {
;         const float mn = upd ? mx : m, alpha = ex2(m - mn); l *= alpha; O[0] = O[0] * alpha; O[1] = O[1] * alpha; m = mn;
;     }
;     const float msub = (m < -1e29f) ? 0.f : m;
;     const f32x16 d = sc - msub;
;     float p[16], ps = 0.f;
; #pragma unroll
;     for (int i = 0; i < 16; ++i) { p[i] = ex2(d[i]); ps += p[i]; }
;     l += ps;
;     const bf16x8 pb0 = pack_p(p), pb1 = pack_p(p + 8);
;     __builtin_amdgcn_s_setprio(1);
;     O[0] = mfma32(vf[0], pb0, O[0]); O[1] = mfma32(vf[1], pb0, O[1]);
;     O[0] = mfma32(vf[2], pb1, O[0]); O[1] = mfma32(vf[3], pb1, O[1]);
;     __builtin_amdgcn_s_setprio(0);
; }
; template <int MODE> __device__ __forceinline__ void flash_run(const bf16x8* kb, const bf16x8* vb, const bf16x8 (&q)[4], int nsteps, const LAS unsigned* list, int base, int t, int t0, int qi, int hi, float& m, float& l, f32x16 (&O)[2]) {
;     ...
;         FR_LOAD(s + 2, kC, vC, x0C, spC, vmC); flash_compute(vmA != 0, kA, vA, q, x0A, spA, m, l, O); if (s + 1 >= nsteps) break;
;         FR_LOAD(s + 3, kA, vA, x0A, spA, vmA); flash_compute(vmB != 0, kB, vB, q, x0B, spB, m, l, O); if (s + 2 >= nsteps) break;
;         FR_LOAD(s + 4, kB, vB, x0B, spB, vmB); flash_compute(vmC != 0, kC, vC, q, x0C, spC, m, l, O);
;     }
.LBB0_883:
	v_cmp_ngt_f32_e32 vcc, s66, v168
	s_lshl_b32 s10, s6, 5
	s_or_b32 s3, s10, 31
	v_cndmask_b32_e32 v146, 0, v168, vcc
	v_sub_f32_e32 v34, v34, v146
	v_sub_f32_e32 v35, v35, v146
	v_exp_f32_e32 v34, v34
	v_sub_f32_e32 v36, v36, v146
	v_exp_f32_e32 v35, v35
	v_sub_f32_e32 v37, v37, v146
	v_exp_f32_e32 v36, v36
	v_sub_f32_e32 v38, v38, v146
	v_exp_f32_e32 v37, v37
	v_sub_f32_e32 v49, v49, v146
	v_sub_f32_e32 v48, v48, v146
	v_sub_f32_e32 v47, v47, v146
	v_sub_f32_e32 v46, v46, v146
	v_sub_f32_e32 v45, v45, v146
	v_sub_f32_e32 v44, v44, v146
	v_sub_f32_e32 v43, v43, v146
	v_sub_f32_e32 v42, v42, v146
	v_sub_f32_e32 v41, v41, v146
	v_sub_f32_e32 v40, v40, v146
	v_sub_f32_e32 v39, v39, v146
	v_add_f32_e32 v146, 0, v34
	v_exp_f32_e32 v38, v38
	v_add_f32_e32 v146, v35, v146
	v_exp_f32_e32 v39, v39
	v_add_f32_e32 v146, v36, v146
	v_exp_f32_e32 v40, v40
	v_add_f32_e32 v146, v37, v146
	v_exp_f32_e32 v41, v41
	s_cmp_gt_i32 s3, s97
	v_add_f32_e32 v146, v38, v146
	v_exp_f32_e32 v42, v42
	s_cselect_b64 s[12:13], -1, 0
	s_cmp_lt_i32 s10, s16
	v_add_f32_e32 v146, v39, v146
	v_exp_f32_e32 v43, v43
	s_cselect_b64 s[18:19], -1, 0
	v_add_f32_e32 v146, v40, v146
	v_exp_f32_e32 v44, v44
	s_or_b64 s[12:13], s[12:13], s[18:19]
	v_add_f32_e32 v146, v41, v146
	v_exp_f32_e32 v45, v45
	s_and_b64 s[12:13], s[12:13], exec
	v_add_f32_e32 v146, v42, v146
	v_exp_f32_e32 v46, v46
	s_cselect_b32 s11, 2, 0
	s_lshl_b32 s5, s4, 5
	v_add_f32_e32 v146, v43, v146
	v_exp_f32_e32 v47, v47
	s_or_b32 s3, s5, 31
	v_add_f32_e32 v146, v44, v146
	v_exp_f32_e32 v48, v48
	s_cmp_gt_i32 s3, s97
	v_add_f32_e32 v146, v45, v146
	v_exp_f32_e32 v49, v49
	s_cselect_b64 s[12:13], -1, 0
	s_cmp_lt_i32 s5, s16
	v_add_f32_e32 v146, v46, v146
	s_cselect_b64 s[18:19], -1, 0
	v_add_f32_e32 v146, v47, v146
	s_or_b64 s[12:13], s[12:13], s[18:19]
	v_add_f32_e32 v146, v48, v146
	s_and_b64 s[12:13], s[12:13], exec
	v_add_f32_e32 v146, v49, v146
	s_cselect_b32 s17, 2, 0
	v_add_f32_e32 v166, v166, v146
	v_cvt_pk_bf16_f32 v34, v34, v35
	v_cvt_pk_bf16_f32 v35, v36, v37
	v_cvt_pk_bf16_f32 v36, v38, v39
	v_cvt_pk_bf16_f32 v37, v40, v41
	v_cvt_pk_bf16_f32 v38, v42, v43
	v_cvt_pk_bf16_f32 v39, v44, v45
	v_cvt_pk_bf16_f32 v40, v46, v47
	v_cvt_pk_bf16_f32 v41, v48, v49
	s_waitcnt vmcnt(19)
	v_mfma_f32_32x32x16_bf16 v[18:33], v[142:145], v[34:37], v[18:33]
	s_waitcnt vmcnt(18)
	v_mfma_f32_32x32x16_bf16 v[2:17], v[138:141], v[34:37], v[2:17]
	s_waitcnt vmcnt(17)
	v_mfma_f32_32x32x16_bf16 v[18:33], v[134:137], v[38:41], v[18:33]
	s_waitcnt vmcnt(16)
	v_mfma_f32_32x32x16_bf16 v[2:17], v[130:133], v[38:41], v[2:17]
	s_add_i32 s3, s1, 1
	s_cmp_gt_i32 s3, s2
	s_cselect_b64 s[12:13], -1, 0
	s_and_b64 vcc, exec, s[12:13]
	s_cbranch_vccz .LBB0_869
	s_branch .LBB0_649
